# GEMM unit start: accumulators zeroed with 64 v_mov_b64 instead of 128 v_mov_b32 (on top of trimmed barrier hand-off)
# speedup vs baseline: 1.0015x; 1.0015x over previous
; template <class Epi, class Sched, bool ALIGN_EPI = false, bool SP2 = false>
; __device__ __forceinline__ void gemm_phase(PG8_LAS unsigned char* lds, const Gemm g, const Sched& S, const Epi& E) {
;     ...
;         const bool has_next = S.next(ui + 1, nxt);
;         const char* nA = has_next ? (const char*)g.A + (size_t)nxt.pm * tstepA : cA; const char* nB = has_next ? (const char*)g.Bt + (size_t)nxt.pn * tstepB : cB;
;     ...
; #pragma unroll
;         for (int a = 0; a < 2; ++a)
; #pragma unroll
;             for (int b = 0; b < 2; ++b)
; #pragma unroll
;                 for (int m = 0; m < 4; ++m)
; #pragma unroll
;                     for (int n = 0; n < 2; ++n) acc[a][b][m][n] = (f32x4){0.f, 0.f, 0.f, 0.f};
;         cur = nxt; cA = nA; cB = nB; ++ui;
.LBB0_243:
	s_ashr_i32 s15, s14, 31
	s_lshl_b64 s[20:21], s[14:15], 19
	s_add_u32 s20, s60, s20
	s_addc_u32 s21, s61, s21
	s_and_b64 s[22:23], s[4:5], exec
	s_cselect_b32 s15, s21, s27
	s_cselect_b32 s62, s20, s26
	s_ashr_i32 s13, s12, 31
	s_lshl_b64 s[22:23], s[12:13], 19
	s_add_u32 s22, s34, s22
	s_addc_u32 s23, s35, s23
	s_and_b64 s[30:31], s[4:5], exec
	s_cselect_b32 s13, s23, s29
	s_cselect_b32 s63, s22, s28
	s_add_u32 s26, s26, 0x40080
	s_addc_u32 s27, s27, 0
	s_add_u32 s66, s28, 0x100
	v_mov_b64_e32 v[0:1], 0
	s_addc_u32 s67, s29, 0
	s_mov_b32 s68, -2
	v_mov_b64_e32 v[2:3], 0
	v_mov_b64_e32 v[8:9], 0
	v_mov_b64_e32 v[10:11], 0
	v_mov_b64_e32 v[16:17], 0
	v_mov_b64_e32 v[18:19], 0
	v_mov_b64_e32 v[24:25], 0
	v_mov_b64_e32 v[26:27], 0
	v_mov_b64_e32 v[32:33], 0
	v_mov_b64_e32 v[34:35], 0
	v_mov_b64_e32 v[40:41], 0
	v_mov_b64_e32 v[42:43], 0
	v_mov_b64_e32 v[48:49], 0
	v_mov_b64_e32 v[50:51], 0
	v_mov_b64_e32 v[56:57], 0
	v_mov_b64_e32 v[58:59], 0
	v_mov_b64_e32 v[4:5], 0
	v_mov_b64_e32 v[6:7], 0
	v_mov_b64_e32 v[12:13], 0
	v_mov_b64_e32 v[14:15], 0
	v_mov_b64_e32 v[20:21], 0
	v_mov_b64_e32 v[22:23], 0
	v_mov_b64_e32 v[28:29], 0
	v_mov_b64_e32 v[30:31], 0
	v_mov_b64_e32 v[36:37], 0
	v_mov_b64_e32 v[38:39], 0
	v_mov_b64_e32 v[44:45], 0
	v_mov_b64_e32 v[46:47], 0
	v_mov_b64_e32 v[52:53], 0
	v_mov_b64_e32 v[54:55], 0
	v_mov_b64_e32 v[60:61], 0
	v_mov_b64_e32 v[62:63], 0
	v_mov_b64_e32 v[64:65], 0
	v_mov_b64_e32 v[66:67], 0
	v_mov_b64_e32 v[72:73], 0
	v_mov_b64_e32 v[74:75], 0
	v_mov_b64_e32 v[80:81], 0
	v_mov_b64_e32 v[82:83], 0
	v_mov_b64_e32 v[88:89], 0
	v_mov_b64_e32 v[90:91], 0
	v_mov_b64_e32 v[96:97], 0
	v_mov_b64_e32 v[98:99], 0
	v_mov_b64_e32 v[112:113], 0
	v_mov_b64_e32 v[114:115], 0
	v_mov_b64_e32 v[120:121], 0
	v_mov_b64_e32 v[122:123], 0
	v_mov_b64_e32 v[124:125], 0
	v_mov_b64_e32 v[126:127], 0
	v_mov_b64_e32 v[68:69], 0
	v_mov_b64_e32 v[70:71], 0
	v_mov_b64_e32 v[76:77], 0
	v_mov_b64_e32 v[78:79], 0
	v_mov_b64_e32 v[84:85], 0
	v_mov_b64_e32 v[86:87], 0
	v_mov_b64_e32 v[92:93], 0
	v_mov_b64_e32 v[94:95], 0
	v_mov_b64_e32 v[100:101], 0
	v_mov_b64_e32 v[102:103], 0
	v_mov_b64_e32 v[104:105], 0
	v_mov_b64_e32 v[106:107], 0
	v_mov_b64_e32 v[108:109], 0
	v_mov_b64_e32 v[110:111], 0
	v_mov_b64_e32 v[116:117], 0
	v_mov_b64_e32 v[118:119], 0

; template <class Epi, class Sched, bool ALIGN_EPI = false, bool SP2 = false>
; __device__ __forceinline__ void gemm_phase(PG8_LAS unsigned char* lds, const Gemm g, const Sched& S, const Epi& E) {
;     ...
; #pragma unroll
;         for (int a = 0; a < 2; ++a)
; #pragma unroll
;             for (int b = 0; b < 2; ++b)
; #pragma unroll
;                 for (int m = 0; m < 4; ++m)
; #pragma unroll
;                     for (int n = 0; n < 2; ++n) acc[a][b][m][n] = (f32x4){0.f, 0.f, 0.f, 0.f};
;         cur = nxt; cA = nA; cB = nB; ++ui;
.LBB0_317:
	s_add_u32 s70, s28, 0x100
	v_mov_b64_e32 v[0:1], 0
	s_addc_u32 s71, s29, 0
	s_mov_b32 s72, -2
	s_waitcnt lgkmcnt(0)
	v_mov_b64_e32 v[2:3], 0
	v_mov_b64_e32 v[4:5], 0
	v_mov_b64_e32 v[6:7], 0
	v_mov_b64_e32 v[16:17], 0
	v_mov_b64_e32 v[18:19], 0
	v_mov_b64_e32 v[20:21], 0
	v_mov_b64_e32 v[22:23], 0
	v_mov_b64_e32 v[32:33], 0
	v_mov_b64_e32 v[34:35], 0
	v_mov_b64_e32 v[36:37], 0
	v_mov_b64_e32 v[38:39], 0
	v_mov_b64_e32 v[48:49], 0
	v_mov_b64_e32 v[50:51], 0
	v_mov_b64_e32 v[52:53], 0
	v_mov_b64_e32 v[54:55], 0
	v_mov_b64_e32 v[8:9], 0
	v_mov_b64_e32 v[10:11], 0
	v_mov_b64_e32 v[12:13], 0
	v_mov_b64_e32 v[14:15], 0
	v_mov_b64_e32 v[24:25], 0
	v_mov_b64_e32 v[26:27], 0
	v_mov_b64_e32 v[28:29], 0
	v_mov_b64_e32 v[30:31], 0
	v_mov_b64_e32 v[40:41], 0
	v_mov_b64_e32 v[42:43], 0
	v_mov_b64_e32 v[44:45], 0
	v_mov_b64_e32 v[46:47], 0
	v_mov_b64_e32 v[56:57], 0
	v_mov_b64_e32 v[58:59], 0
	v_mov_b64_e32 v[60:61], 0
	v_mov_b64_e32 v[62:63], 0
	v_mov_b64_e32 v[64:65], 0
	v_mov_b64_e32 v[66:67], 0
	v_mov_b64_e32 v[68:69], 0
	v_mov_b64_e32 v[70:71], 0
	v_mov_b64_e32 v[80:81], 0
	v_mov_b64_e32 v[82:83], 0
	v_mov_b64_e32 v[84:85], 0
	v_mov_b64_e32 v[86:87], 0
	v_mov_b64_e32 v[96:97], 0
	v_mov_b64_e32 v[98:99], 0
	v_mov_b64_e32 v[100:101], 0
	v_mov_b64_e32 v[102:103], 0
	v_mov_b64_e32 v[112:113], 0
	v_mov_b64_e32 v[114:115], 0
	v_mov_b64_e32 v[116:117], 0
	v_mov_b64_e32 v[118:119], 0
	v_mov_b64_e32 v[72:73], 0
	v_mov_b64_e32 v[74:75], 0
	v_mov_b64_e32 v[76:77], 0
	v_mov_b64_e32 v[78:79], 0
	v_mov_b64_e32 v[88:89], 0
	v_mov_b64_e32 v[90:91], 0
	v_mov_b64_e32 v[92:93], 0
	v_mov_b64_e32 v[94:95], 0
	v_mov_b64_e32 v[104:105], 0
	v_mov_b64_e32 v[106:107], 0
	v_mov_b64_e32 v[108:109], 0
	v_mov_b64_e32 v[110:111], 0
	v_mov_b64_e32 v[120:121], 0
	v_mov_b64_e32 v[122:123], 0
	v_mov_b64_e32 v[124:125], 0
	v_mov_b64_e32 v[126:127], 0

; template <class Epi, class Sched, bool ALIGN_EPI = false, bool SP2 = false>
; __device__ __forceinline__ void gemm_phase(PG8_LAS unsigned char* lds, const Gemm g, const Sched& S, const Epi& E) {
;     ...
; #pragma unroll
;         for (int a = 0; a < 2; ++a)
; #pragma unroll
;             for (int b = 0; b < 2; ++b)
; #pragma unroll
;                 for (int m = 0; m < 4; ++m)
; #pragma unroll
;                     for (int n = 0; n < 2; ++n) acc[a][b][m][n] = (f32x4){0.f, 0.f, 0.f, 0.f};
;         cur = nxt; cA = nA; cB = nB; ++ui;
.LBB0_523:
	s_add_u32 s74, s30, 0x100
	v_mov_b64_e32 v[0:1], 0
	s_addc_u32 s75, s31, 0
	s_mov_b32 s76, -2
	v_mov_b64_e32 v[2:3], 0
	v_mov_b64_e32 v[4:5], 0
	v_mov_b64_e32 v[6:7], 0
	v_mov_b64_e32 v[16:17], 0
	v_mov_b64_e32 v[18:19], 0
	v_mov_b64_e32 v[20:21], 0
	v_mov_b64_e32 v[22:23], 0
	v_mov_b64_e32 v[32:33], 0
	v_mov_b64_e32 v[34:35], 0
	v_mov_b64_e32 v[36:37], 0
	v_mov_b64_e32 v[38:39], 0
	v_mov_b64_e32 v[48:49], 0
	v_mov_b64_e32 v[50:51], 0
	v_mov_b64_e32 v[52:53], 0
	v_mov_b64_e32 v[54:55], 0
	v_mov_b64_e32 v[8:9], 0
	v_mov_b64_e32 v[10:11], 0
	v_mov_b64_e32 v[12:13], 0
	v_mov_b64_e32 v[14:15], 0
	v_mov_b64_e32 v[24:25], 0
	v_mov_b64_e32 v[26:27], 0
	v_mov_b64_e32 v[28:29], 0
	v_mov_b64_e32 v[30:31], 0
	v_mov_b64_e32 v[40:41], 0
	v_mov_b64_e32 v[42:43], 0
	v_mov_b64_e32 v[44:45], 0
	v_mov_b64_e32 v[46:47], 0
	v_mov_b64_e32 v[56:57], 0
	v_mov_b64_e32 v[58:59], 0
	v_mov_b64_e32 v[60:61], 0
	v_mov_b64_e32 v[62:63], 0
	v_mov_b64_e32 v[64:65], 0
	v_mov_b64_e32 v[66:67], 0
	v_mov_b64_e32 v[68:69], 0
	v_mov_b64_e32 v[70:71], 0
	v_mov_b64_e32 v[80:81], 0
	v_mov_b64_e32 v[82:83], 0
	v_mov_b64_e32 v[84:85], 0
	v_mov_b64_e32 v[86:87], 0
	v_mov_b64_e32 v[96:97], 0
	v_mov_b64_e32 v[98:99], 0
	v_mov_b64_e32 v[100:101], 0
	v_mov_b64_e32 v[102:103], 0
	v_mov_b64_e32 v[112:113], 0
	v_mov_b64_e32 v[114:115], 0
	v_mov_b64_e32 v[116:117], 0
	v_mov_b64_e32 v[118:119], 0
	v_mov_b64_e32 v[72:73], 0
	v_mov_b64_e32 v[74:75], 0
	v_mov_b64_e32 v[76:77], 0
	v_mov_b64_e32 v[78:79], 0
	v_mov_b64_e32 v[88:89], 0
	v_mov_b64_e32 v[90:91], 0
	v_mov_b64_e32 v[92:93], 0
	v_mov_b64_e32 v[94:95], 0
	v_mov_b64_e32 v[104:105], 0
	v_mov_b64_e32 v[106:107], 0
	v_mov_b64_e32 v[108:109], 0
	v_mov_b64_e32 v[110:111], 0
	v_mov_b64_e32 v[120:121], 0
	v_mov_b64_e32 v[122:123], 0
	v_mov_b64_e32 v[124:125], 0
	v_mov_b64_e32 v[126:127], 0

; template <class Epi, class Sched, bool ALIGN_EPI = false, bool SP2 = false>
; __device__ __forceinline__ void gemm_phase(PG8_LAS unsigned char* lds, const Gemm g, const Sched& S, const Epi& E) {
;     ...
;         const bool has_next = S.next(ui + 1, nxt);
;         const char* nA = has_next ? (const char*)g.A + (size_t)nxt.pm * tstepA : cA; const char* nB = has_next ? (const char*)g.Bt + (size_t)nxt.pn * tstepB : cB;
;     ...
; #pragma unroll
;         for (int a = 0; a < 2; ++a)
; #pragma unroll
;             for (int b = 0; b < 2; ++b)
; #pragma unroll
;                 for (int m = 0; m < 4; ++m)
; #pragma unroll
;                     for (int n = 0; n < 2; ++n) acc[a][b][m][n] = (f32x4){0.f, 0.f, 0.f, 0.f};
;         cur = nxt; cA = nA; cB = nB; ++ui;
.LBB0_541:
	s_ashr_i32 s25, s24, 31
	s_lshl_b64 s[28:29], s[24:25], 17
	s_add_u32 s28, s66, s28
	s_addc_u32 s29, s67, s29
	s_and_b64 s[8:9], s[8:9], exec
	v_mov_b64_e32 v[0:1], 0
	s_cselect_b32 s25, s29, s31
	s_cselect_b32 s89, s28, s30
	s_mov_b32 s38, 0
	s_mov_b64 s[8:9], -1
	s_mov_b64 s[36:37], 0
	v_mov_b64_e32 v[2:3], 0
	v_mov_b64_e32 v[4:5], 0
	v_mov_b64_e32 v[6:7], 0
	v_mov_b64_e32 v[16:17], 0
	v_mov_b64_e32 v[18:19], 0
	v_mov_b64_e32 v[20:21], 0
	v_mov_b64_e32 v[22:23], 0
	v_mov_b64_e32 v[32:33], 0
	v_mov_b64_e32 v[34:35], 0
	v_mov_b64_e32 v[36:37], 0
	v_mov_b64_e32 v[38:39], 0
	v_mov_b64_e32 v[48:49], 0
	v_mov_b64_e32 v[50:51], 0
	v_mov_b64_e32 v[52:53], 0
	v_mov_b64_e32 v[54:55], 0
	v_mov_b64_e32 v[8:9], 0
	v_mov_b64_e32 v[10:11], 0
	v_mov_b64_e32 v[12:13], 0
	v_mov_b64_e32 v[14:15], 0
	v_mov_b64_e32 v[24:25], 0
	v_mov_b64_e32 v[26:27], 0
	v_mov_b64_e32 v[28:29], 0
	v_mov_b64_e32 v[30:31], 0
	v_mov_b64_e32 v[40:41], 0
	v_mov_b64_e32 v[42:43], 0
	v_mov_b64_e32 v[44:45], 0
	v_mov_b64_e32 v[46:47], 0
	v_mov_b64_e32 v[56:57], 0
	v_mov_b64_e32 v[58:59], 0
	v_mov_b64_e32 v[60:61], 0
	v_mov_b64_e32 v[62:63], 0
	v_mov_b64_e32 v[64:65], 0
	v_mov_b64_e32 v[66:67], 0
	v_mov_b64_e32 v[68:69], 0
	v_mov_b64_e32 v[70:71], 0
	v_mov_b64_e32 v[80:81], 0
	v_mov_b64_e32 v[82:83], 0
	v_mov_b64_e32 v[84:85], 0
	v_mov_b64_e32 v[86:87], 0
	v_mov_b64_e32 v[96:97], 0
	v_mov_b64_e32 v[98:99], 0
	v_mov_b64_e32 v[100:101], 0
	v_mov_b64_e32 v[102:103], 0
	v_mov_b64_e32 v[112:113], 0
	v_mov_b64_e32 v[114:115], 0
	v_mov_b64_e32 v[116:117], 0
	v_mov_b64_e32 v[118:119], 0
	v_mov_b64_e32 v[72:73], 0
	v_mov_b64_e32 v[74:75], 0
	v_mov_b64_e32 v[76:77], 0
	v_mov_b64_e32 v[78:79], 0
	v_mov_b64_e32 v[88:89], 0
	v_mov_b64_e32 v[90:91], 0
	v_mov_b64_e32 v[92:93], 0
	v_mov_b64_e32 v[94:95], 0
	v_mov_b64_e32 v[104:105], 0
	v_mov_b64_e32 v[106:107], 0
	v_mov_b64_e32 v[108:109], 0
	v_mov_b64_e32 v[110:111], 0
	v_mov_b64_e32 v[120:121], 0
	v_mov_b64_e32 v[122:123], 0
	v_mov_b64_e32 v[124:125], 0
	v_mov_b64_e32 v[126:127], 0

; template <class Epi, class Sched, bool ALIGN_EPI = false, bool SP2 = false>
; __device__ __forceinline__ void gemm_phase(PG8_LAS unsigned char* lds, const Gemm g, const Sched& S, const Epi& E) {
;     ...
;         const bool has_next = S.next(ui + 1, nxt);
;         const char* nA = has_next ? (const char*)g.A + (size_t)nxt.pm * tstepA : cA; const char* nB = has_next ? (const char*)g.Bt + (size_t)nxt.pn * tstepB : cB;
;     ...
; #pragma unroll
;         for (int a = 0; a < 2; ++a)
; #pragma unroll
;             for (int b = 0; b < 2; ++b)
; #pragma unroll
;                 for (int m = 0; m < 4; ++m)
; #pragma unroll
;                     for (int n = 0; n < 2; ++n) acc[a][b][m][n] = (f32x4){0.f, 0.f, 0.f, 0.f};
;         cur = nxt; cA = nA; cB = nB; ++ui;
.LBB0_970:
	s_ashr_i32 s21, s20, 31
	s_lshl_b64 s[22:23], s[20:21], 19
	s_add_u32 s22, s62, s22
	s_addc_u32 s23, s63, s23
	s_and_b64 s[24:25], s[8:9], exec
	s_cselect_b32 s21, s23, s31
	s_cselect_b32 s27, s22, s30
	s_ashr_i32 s19, s18, 31
	s_lshl_b64 s[24:25], s[18:19], 19
	s_add_u32 s24, s3, s24
	s_addc_u32 s25, s38, s25
	s_and_b64 s[36:37], s[8:9], exec
	s_cselect_b32 s19, s25, s35
	s_cselect_b32 s68, s24, s34
	s_add_u32 s30, s30, 0x40080
	s_addc_u32 s31, s31, 0
	s_add_u32 s69, s34, 0x100
	v_mov_b64_e32 v[0:1], 0
	s_addc_u32 s73, s35, 0
	s_mov_b32 s74, -2
	s_waitcnt lgkmcnt(0)
	v_mov_b64_e32 v[2:3], 0
	v_mov_b64_e32 v[4:5], 0
	v_mov_b64_e32 v[6:7], 0
	v_mov_b64_e32 v[16:17], 0
	s_waitcnt vmcnt(0)
	v_mov_b64_e32 v[18:19], 0
	v_mov_b64_e32 v[20:21], 0
	v_mov_b64_e32 v[22:23], 0
	v_mov_b64_e32 v[32:33], 0
	v_mov_b64_e32 v[34:35], 0
	v_mov_b64_e32 v[36:37], 0
	v_mov_b64_e32 v[38:39], 0
	v_mov_b64_e32 v[48:49], 0
	v_mov_b64_e32 v[50:51], 0
	v_mov_b64_e32 v[52:53], 0
	v_mov_b64_e32 v[54:55], 0
	v_mov_b64_e32 v[8:9], 0
	v_mov_b64_e32 v[10:11], 0
	v_mov_b64_e32 v[12:13], 0
	v_mov_b64_e32 v[14:15], 0
	v_mov_b64_e32 v[24:25], 0
	v_mov_b64_e32 v[26:27], 0
	v_mov_b64_e32 v[28:29], 0
	v_mov_b64_e32 v[30:31], 0
	v_mov_b64_e32 v[40:41], 0
	v_mov_b64_e32 v[42:43], 0
	v_mov_b64_e32 v[44:45], 0
	v_mov_b64_e32 v[46:47], 0
	v_mov_b64_e32 v[56:57], 0
	v_mov_b64_e32 v[58:59], 0
	v_mov_b64_e32 v[60:61], 0
	v_mov_b64_e32 v[62:63], 0
	v_mov_b64_e32 v[64:65], 0
	v_mov_b64_e32 v[66:67], 0
	v_mov_b64_e32 v[68:69], 0
	v_mov_b64_e32 v[70:71], 0
	v_mov_b64_e32 v[80:81], 0
	v_mov_b64_e32 v[82:83], 0
	v_mov_b64_e32 v[84:85], 0
	v_mov_b64_e32 v[86:87], 0
	v_mov_b64_e32 v[96:97], 0
	v_mov_b64_e32 v[98:99], 0
	v_mov_b64_e32 v[100:101], 0
	v_mov_b64_e32 v[102:103], 0
	v_mov_b64_e32 v[112:113], 0
	v_mov_b64_e32 v[114:115], 0
	v_mov_b64_e32 v[116:117], 0
	v_mov_b64_e32 v[118:119], 0
	v_mov_b64_e32 v[72:73], 0
	v_mov_b64_e32 v[74:75], 0
	v_mov_b64_e32 v[76:77], 0
	v_mov_b64_e32 v[78:79], 0
	v_mov_b64_e32 v[88:89], 0
	v_mov_b64_e32 v[90:91], 0
	v_mov_b64_e32 v[92:93], 0
	v_mov_b64_e32 v[94:95], 0
	v_mov_b64_e32 v[104:105], 0
	v_mov_b64_e32 v[106:107], 0
	v_mov_b64_e32 v[108:109], 0
	v_mov_b64_e32 v[110:111], 0
	v_mov_b64_e32 v[120:121], 0
	v_mov_b64_e32 v[122:123], 0
	v_mov_b64_e32 v[124:125], 0
	v_mov_b64_e32 v[126:127], 0

; template <class Epi, class Sched, bool ALIGN_EPI = false, bool SP2 = false>
; __device__ __forceinline__ void gemm_phase(PG8_LAS unsigned char* lds, const Gemm g, const Sched& S, const Epi& E) {
;     ...
;         const bool has_next = S.next(ui + 1, nxt);
;         const char* nA = has_next ? (const char*)g.A + (size_t)nxt.pm * tstepA : cA; const char* nB = has_next ? (const char*)g.Bt + (size_t)nxt.pn * tstepB : cB;
;     ...
; #pragma unroll
;         for (int a = 0; a < 2; ++a)
; #pragma unroll
;             for (int b = 0; b < 2; ++b)
; #pragma unroll
;                 for (int m = 0; m < 4; ++m)
; #pragma unroll
;                     for (int n = 0; n < 2; ++n) acc[a][b][m][n] = (f32x4){0.f, 0.f, 0.f, 0.f};
;         cur = nxt; cA = nA; cB = nB; ++ui;
.LBB0_1054:
	s_ashr_i32 s19, s18, 31
	s_lshl_b64 s[20:21], s[18:19], 19
	s_add_u32 s20, s60, s20
	s_addc_u32 s21, s61, s21
	s_and_b64 s[22:23], s[6:7], exec
	s_cselect_b32 s19, s21, s27
	s_cselect_b32 s49, s20, s26
	s_ashr_i32 s17, s16, 31
	s_lshl_b64 s[22:23], s[16:17], 19
	s_add_u32 s22, s3, s22
	s_addc_u32 s23, s34, s23
	s_and_b64 s[30:31], s[6:7], exec
	s_cselect_b32 s17, s23, s29
	s_cselect_b32 s66, s22, s28
	s_add_u32 s26, s26, 0x40080
	s_addc_u32 s27, s27, 0
	s_add_u32 s67, s28, 0x100
	v_mov_b64_e32 v[0:1], 0
	s_addc_u32 s68, s29, 0
	s_mov_b32 s69, -2
	v_mov_b64_e32 v[2:3], 0
	v_mov_b64_e32 v[8:9], 0
	v_mov_b64_e32 v[10:11], 0
	v_mov_b64_e32 v[16:17], 0
	s_waitcnt vmcnt(0)
	v_mov_b64_e32 v[18:19], 0
	v_mov_b64_e32 v[24:25], 0
	v_mov_b64_e32 v[26:27], 0
	v_mov_b64_e32 v[32:33], 0
	v_mov_b64_e32 v[34:35], 0
	v_mov_b64_e32 v[40:41], 0
	v_mov_b64_e32 v[42:43], 0
	v_mov_b64_e32 v[48:49], 0
	v_mov_b64_e32 v[50:51], 0
	v_mov_b64_e32 v[56:57], 0
	v_mov_b64_e32 v[58:59], 0
	v_mov_b64_e32 v[4:5], 0
	v_mov_b64_e32 v[6:7], 0
	v_mov_b64_e32 v[12:13], 0
	v_mov_b64_e32 v[14:15], 0
	v_mov_b64_e32 v[20:21], 0
	v_mov_b64_e32 v[22:23], 0
	v_mov_b64_e32 v[28:29], 0
	v_mov_b64_e32 v[30:31], 0
	v_mov_b64_e32 v[36:37], 0
	v_mov_b64_e32 v[38:39], 0
	v_mov_b64_e32 v[44:45], 0
	v_mov_b64_e32 v[46:47], 0
	v_mov_b64_e32 v[52:53], 0
	v_mov_b64_e32 v[54:55], 0
	v_mov_b64_e32 v[60:61], 0
	v_mov_b64_e32 v[62:63], 0
	v_mov_b64_e32 v[64:65], 0
	v_mov_b64_e32 v[66:67], 0
	v_mov_b64_e32 v[72:73], 0
	v_mov_b64_e32 v[74:75], 0
	v_mov_b64_e32 v[80:81], 0
	v_mov_b64_e32 v[82:83], 0
	v_mov_b64_e32 v[88:89], 0
	v_mov_b64_e32 v[90:91], 0
	v_mov_b64_e32 v[96:97], 0
	v_mov_b64_e32 v[98:99], 0
	v_mov_b64_e32 v[104:105], 0
	v_mov_b64_e32 v[106:107], 0
	v_mov_b64_e32 v[120:121], 0
	v_mov_b64_e32 v[122:123], 0
	v_mov_b64_e32 v[124:125], 0
	v_mov_b64_e32 v[126:127], 0
	v_mov_b64_e32 v[68:69], 0
	v_mov_b64_e32 v[70:71], 0
	v_mov_b64_e32 v[76:77], 0
	v_mov_b64_e32 v[78:79], 0
	v_mov_b64_e32 v[84:85], 0
	v_mov_b64_e32 v[86:87], 0
	v_mov_b64_e32 v[92:93], 0
	v_mov_b64_e32 v[94:95], 0
	v_mov_b64_e32 v[100:101], 0
	v_mov_b64_e32 v[102:103], 0
	v_mov_b64_e32 v[108:109], 0
	v_mov_b64_e32 v[110:111], 0
	v_mov_b64_e32 v[112:113], 0
	v_mov_b64_e32 v[114:115], 0
	v_mov_b64_e32 v[116:117], 0
	v_mov_b64_e32 v[118:119], 0

; template <class Epi, class Sched, bool ALIGN_EPI = false, bool SP2 = false>
; __device__ __forceinline__ void gemm_phase(PG8_LAS unsigned char* lds, const Gemm g, const Sched& S, const Epi& E) {
;     ...
; #pragma unroll
;         for (int a = 0; a < 2; ++a)
; #pragma unroll
;             for (int b = 0; b < 2; ++b)
; #pragma unroll
;                 for (int m = 0; m < 4; ++m)
; #pragma unroll
;                     for (int n = 0; n < 2; ++n) acc[a][b][m][n] = (f32x4){0.f, 0.f, 0.f, 0.f};
;         cur = nxt; cA = nA; cB = nB; ++ui;
.LBB0_1128:
	s_add_u32 s67, s24, 0x100
	v_mov_b64_e32 v[0:1], 0
	s_addc_u32 s68, s25, 0
	s_mov_b32 s69, -2
	s_waitcnt lgkmcnt(0)
	v_mov_b64_e32 v[2:3], 0
	v_mov_b64_e32 v[4:5], 0
	v_mov_b64_e32 v[6:7], 0
	v_mov_b64_e32 v[16:17], 0
	s_waitcnt vmcnt(0)
	v_mov_b64_e32 v[18:19], 0
	v_mov_b64_e32 v[20:21], 0
	v_mov_b64_e32 v[22:23], 0
	v_mov_b64_e32 v[32:33], 0
	v_mov_b64_e32 v[34:35], 0
	v_mov_b64_e32 v[36:37], 0
	v_mov_b64_e32 v[38:39], 0
	v_mov_b64_e32 v[48:49], 0
	v_mov_b64_e32 v[50:51], 0
	v_mov_b64_e32 v[52:53], 0
	v_mov_b64_e32 v[54:55], 0
	v_mov_b64_e32 v[8:9], 0
	v_mov_b64_e32 v[10:11], 0
	v_mov_b64_e32 v[12:13], 0
	v_mov_b64_e32 v[14:15], 0
	v_mov_b64_e32 v[24:25], 0
	v_mov_b64_e32 v[26:27], 0
	v_mov_b64_e32 v[28:29], 0
	v_mov_b64_e32 v[30:31], 0
	v_mov_b64_e32 v[40:41], 0
	v_mov_b64_e32 v[42:43], 0
	v_mov_b64_e32 v[44:45], 0
	v_mov_b64_e32 v[46:47], 0
	v_mov_b64_e32 v[56:57], 0
	v_mov_b64_e32 v[58:59], 0
	v_mov_b64_e32 v[60:61], 0
	v_mov_b64_e32 v[62:63], 0
	v_mov_b64_e32 v[64:65], 0
	v_mov_b64_e32 v[66:67], 0
	v_mov_b64_e32 v[68:69], 0
	v_mov_b64_e32 v[70:71], 0
	v_mov_b64_e32 v[80:81], 0
	v_mov_b64_e32 v[82:83], 0
	v_mov_b64_e32 v[84:85], 0
	v_mov_b64_e32 v[86:87], 0
	v_mov_b64_e32 v[96:97], 0
	v_mov_b64_e32 v[98:99], 0
	v_mov_b64_e32 v[100:101], 0
	v_mov_b64_e32 v[102:103], 0
	v_mov_b64_e32 v[112:113], 0
	v_mov_b64_e32 v[114:115], 0
	v_mov_b64_e32 v[116:117], 0
	v_mov_b64_e32 v[118:119], 0
	v_mov_b64_e32 v[72:73], 0
	v_mov_b64_e32 v[74:75], 0
	v_mov_b64_e32 v[76:77], 0
	v_mov_b64_e32 v[78:79], 0
	v_mov_b64_e32 v[88:89], 0
	v_mov_b64_e32 v[90:91], 0
	v_mov_b64_e32 v[92:93], 0
	v_mov_b64_e32 v[94:95], 0
	v_mov_b64_e32 v[104:105], 0
	v_mov_b64_e32 v[106:107], 0
	v_mov_b64_e32 v[108:109], 0
	v_mov_b64_e32 v[110:111], 0
	v_mov_b64_e32 v[120:121], 0
	v_mov_b64_e32 v[122:123], 0
	v_mov_b64_e32 v[124:125], 0
	v_mov_b64_e32 v[126:127], 0

; template <class Epi, class Sched, bool ALIGN_EPI = false, bool SP2 = false>
; __device__ __forceinline__ void gemm_phase(PG8_LAS unsigned char* lds, const Gemm g, const Sched& S, const Epi& E) {
;     ...
;         const bool has_next = S.next(ui + 1, nxt);
;         const char* nA = has_next ? (const char*)g.A + (size_t)nxt.pm * tstepA : cA; const char* nB = has_next ? (const char*)g.Bt + (size_t)nxt.pn * tstepB : cB;
;     ...
; #pragma unroll
;         for (int a = 0; a < 2; ++a)
; #pragma unroll
;             for (int b = 0; b < 2; ++b)
; #pragma unroll
;                 for (int m = 0; m < 4; ++m)
; #pragma unroll
;                     for (int n = 0; n < 2; ++n) acc[a][b][m][n] = (f32x4){0.f, 0.f, 0.f, 0.f};
;         cur = nxt; cA = nA; cB = nB; ++ui;
.LBB0_1160:
	s_ashr_i32 s25, s24, 31
	s_lshl_b64 s[26:27], s[24:25], 17
	s_add_u32 s26, s68, s26
	s_addc_u32 s27, s69, s27
	s_and_b64 s[28:29], s[6:7], exec
	s_cselect_b32 s25, s27, s37
	s_cselect_b32 s89, s26, s36
	s_ashr_i32 s23, s22, 31
	s_lshl_b64 s[28:29], s[22:23], 17
	s_add_u32 s28, s3, s28
	s_addc_u32 s29, s66, s29
	s_and_b64 s[38:39], s[6:7], exec
	v_mov_b64_e32 v[0:1], 0
	s_cselect_b32 s23, s29, s35
	s_cselect_b32 s90, s28, s34
	s_mov_b32 s42, 0
	s_mov_b64 s[38:39], -1
	s_mov_b64 s[40:41], 0
	v_mov_b64_e32 v[2:3], 0
	v_mov_b64_e32 v[4:5], 0
	v_mov_b64_e32 v[6:7], 0
	v_mov_b64_e32 v[8:9], 0
	v_mov_b64_e32 v[10:11], 0
	v_mov_b64_e32 v[16:17], 0
	v_mov_b64_e32 v[18:19], 0
	v_mov_b64_e32 v[24:25], 0
	v_mov_b64_e32 v[26:27], 0
	v_mov_b64_e32 v[32:33], 0
	v_mov_b64_e32 v[34:35], 0
	v_mov_b64_e32 v[40:41], 0
	v_mov_b64_e32 v[42:43], 0
	v_mov_b64_e32 v[48:49], 0
	v_mov_b64_e32 v[50:51], 0
	v_mov_b64_e32 v[12:13], 0
	v_mov_b64_e32 v[14:15], 0
	v_mov_b64_e32 v[20:21], 0
	v_mov_b64_e32 v[22:23], 0
	v_mov_b64_e32 v[28:29], 0
	v_mov_b64_e32 v[30:31], 0
	v_mov_b64_e32 v[36:37], 0
	v_mov_b64_e32 v[38:39], 0
	v_mov_b64_e32 v[44:45], 0
	v_mov_b64_e32 v[46:47], 0
	v_mov_b64_e32 v[52:53], 0
	v_mov_b64_e32 v[54:55], 0
	v_mov_b64_e32 v[56:57], 0
	v_mov_b64_e32 v[58:59], 0
	v_mov_b64_e32 v[60:61], 0
	v_mov_b64_e32 v[62:63], 0
	v_mov_b64_e32 v[64:65], 0
	v_mov_b64_e32 v[66:67], 0
	v_mov_b64_e32 v[68:69], 0
	v_mov_b64_e32 v[70:71], 0
	v_mov_b64_e32 v[72:73], 0
	v_mov_b64_e32 v[74:75], 0
	v_mov_b64_e32 v[80:81], 0
	v_mov_b64_e32 v[82:83], 0
	v_mov_b64_e32 v[88:89], 0
	v_mov_b64_e32 v[90:91], 0
	v_mov_b64_e32 v[96:97], 0
	v_mov_b64_e32 v[98:99], 0
	v_mov_b64_e32 v[104:105], 0
	v_mov_b64_e32 v[106:107], 0
	v_mov_b64_e32 v[112:113], 0
	v_mov_b64_e32 v[114:115], 0
	v_mov_b64_e32 v[76:77], 0
	v_mov_b64_e32 v[78:79], 0
	v_mov_b64_e32 v[84:85], 0
	v_mov_b64_e32 v[86:87], 0
	v_mov_b64_e32 v[92:93], 0
	v_mov_b64_e32 v[94:95], 0
	v_mov_b64_e32 v[100:101], 0
	v_mov_b64_e32 v[102:103], 0
	v_mov_b64_e32 v[108:109], 0
	v_mov_b64_e32 v[110:111], 0
	v_mov_b64_e32 v[116:117], 0
	v_mov_b64_e32 v[118:119], 0
	v_mov_b64_e32 v[120:121], 0
	v_mov_b64_e32 v[122:123], 0
	v_mov_b64_e32 v[124:125], 0
	v_mov_b64_e32 v[126:127], 0

; template <class Epi, class Sched, bool ALIGN_EPI = false, bool SP2 = false>
; __device__ __forceinline__ void gemm_phase(PG8_LAS unsigned char* lds, const Gemm g, const Sched& S, const Epi& E) {
;     ...
;         const bool has_next = S.next(ui + 1, nxt);
;         const char* nA = has_next ? (const char*)g.A + (size_t)nxt.pm * tstepA : cA; const char* nB = has_next ? (const char*)g.Bt + (size_t)nxt.pn * tstepB : cB;
;     ...
; #pragma unroll
;         for (int a = 0; a < 2; ++a)
; #pragma unroll
;             for (int b = 0; b < 2; ++b)
; #pragma unroll
;                 for (int m = 0; m < 4; ++m)
; #pragma unroll
;                     for (int n = 0; n < 2; ++n) acc[a][b][m][n] = (f32x4){0.f, 0.f, 0.f, 0.f};
;         cur = nxt; cA = nA; cB = nB; ++ui;
.LBB0_1230:
	s_ashr_i32 s21, s20, 31
	s_lshl_b64 s[22:23], s[20:21], 19
	s_add_u32 s22, s60, s22
	s_addc_u32 s23, s61, s23
	s_and_b64 s[24:25], s[6:7], exec
	s_cselect_b32 s21, s23, s31
	s_cselect_b32 s27, s22, s30
	s_ashr_i32 s19, s18, 31
	s_lshl_b64 s[24:25], s[18:19], 19
	s_add_u32 s24, s3, s24
	s_addc_u32 s25, s38, s25
	s_and_b64 s[36:37], s[6:7], exec
	s_cselect_b32 s19, s25, s35
	s_cselect_b32 s66, s24, s34
	s_add_u32 s30, s30, 0x40080
	s_addc_u32 s31, s31, 0
	s_add_u32 s67, s34, 0x100
	v_mov_b64_e32 v[0:1], 0
	s_addc_u32 s68, s35, 0
	s_mov_b32 s69, -2
	s_waitcnt lgkmcnt(0)
	v_mov_b64_e32 v[2:3], 0
	v_mov_b64_e32 v[4:5], 0
	v_mov_b64_e32 v[6:7], 0
	v_mov_b64_e32 v[16:17], 0
	v_mov_b64_e32 v[18:19], 0
	v_mov_b64_e32 v[20:21], 0
	v_mov_b64_e32 v[22:23], 0
	v_mov_b64_e32 v[32:33], 0
	v_mov_b64_e32 v[34:35], 0
	v_mov_b64_e32 v[36:37], 0
	v_mov_b64_e32 v[38:39], 0
	v_mov_b64_e32 v[48:49], 0
	v_mov_b64_e32 v[50:51], 0
	v_mov_b64_e32 v[52:53], 0
	v_mov_b64_e32 v[54:55], 0
	v_mov_b64_e32 v[8:9], 0
	v_mov_b64_e32 v[10:11], 0
	v_mov_b64_e32 v[12:13], 0
	v_mov_b64_e32 v[14:15], 0
	v_mov_b64_e32 v[24:25], 0
	v_mov_b64_e32 v[26:27], 0
	v_mov_b64_e32 v[28:29], 0
	v_mov_b64_e32 v[30:31], 0
	v_mov_b64_e32 v[40:41], 0
	v_mov_b64_e32 v[42:43], 0
	v_mov_b64_e32 v[44:45], 0
	v_mov_b64_e32 v[46:47], 0
	v_mov_b64_e32 v[56:57], 0
	v_mov_b64_e32 v[58:59], 0
	v_mov_b64_e32 v[60:61], 0
	v_mov_b64_e32 v[62:63], 0
	v_mov_b64_e32 v[64:65], 0
	v_mov_b64_e32 v[66:67], 0
	v_mov_b64_e32 v[68:69], 0
	v_mov_b64_e32 v[70:71], 0
	v_mov_b64_e32 v[80:81], 0
	v_mov_b64_e32 v[82:83], 0
	v_mov_b64_e32 v[84:85], 0
	v_mov_b64_e32 v[86:87], 0
	v_mov_b64_e32 v[96:97], 0
	v_mov_b64_e32 v[98:99], 0
	v_mov_b64_e32 v[100:101], 0
	v_mov_b64_e32 v[102:103], 0
	v_mov_b64_e32 v[120:121], 0
	v_mov_b64_e32 v[122:123], 0
	v_mov_b64_e32 v[124:125], 0
	v_mov_b64_e32 v[126:127], 0
	v_mov_b64_e32 v[72:73], 0
	v_mov_b64_e32 v[74:75], 0
	v_mov_b64_e32 v[76:77], 0
	v_mov_b64_e32 v[78:79], 0
	v_mov_b64_e32 v[88:89], 0
	v_mov_b64_e32 v[90:91], 0
	v_mov_b64_e32 v[92:93], 0
	v_mov_b64_e32 v[94:95], 0
	v_mov_b64_e32 v[104:105], 0
	v_mov_b64_e32 v[106:107], 0
	v_mov_b64_e32 v[108:109], 0
	v_mov_b64_e32 v[110:111], 0
	v_mov_b64_e32 v[132:133], 0
	v_mov_b64_e32 v[134:135], 0
	v_mov_b64_e32 v[136:137], 0
	v_mov_b64_e32 v[138:139], 0
